# slot != 0 wave priority through mixers phase A (page streaming and compute items), slot-0 priority in attention/queue and LayerNorm phases
# speedup vs baseline: 1.0169x; 1.0012x over previous
.LBB0_332:
	s_setprio 0
	s_cmp_eq_u32 s101, 3
	s_cbranch_scc1 .Lma_fin
	s_getreg_b32 s100, hwreg(HW_REG_HW_ID, 0, 4)
	s_cmp_lg_u32 s100, 0
	s_cbranch_scc0 .Lprio_done_s3
	s_setprio 1
